# attention: K/V staging (vmcnt wait + ds_writes + next global loads) moved 4 MFMAs later in the tile (behind the PV MFMAs, into the QK MFMA gaps)
# baseline (speedup 1.0000x reference)
; DI void attn_item(const Ctx& c, int item, bf16* lds) {
;     ...
;     if (kt + 1 < ntile) {
;       const bf16* kn = Kb + (size_t)(kt + 1) * 64 * 96;
;       const bf16* vn = Vb + (kt + 1) * 64;
; #pragma unroll
;       for (int i = 0; i < 3; ++i) rk[i] = *(const u32x4*)(kn + (koff + 2048u * i));
; #pragma unroll
;       for (int i = 0; i < 2; ++i) rv[i] = *(const u32x4*)(vn + (voff + (unsigned)(32 * T) * i));
;     }
; #pragma unroll
;     for (int qs = 0; qs < 2; ++qs) {
;       __builtin_amdgcn_sched_barrier(0);
;       f32x16 st[2];
;       {
;         f32x16 zz;
; #pragma unroll
;         for (int i = 0; i < 16; ++i) zz[i] = 0.f;
; #pragma unroll
;         for (int mt = 0; mt < 2; ++mt)
; #pragma unroll
;           for (int s = 0; s < 6; ++s) {
;             const bf16x8 a = *(const bf16x8*)(Ks + (32 * mt + r) * AK_LD + 16 * s + 8 * hh);
;             const bf16x8 qb_ = (qs == 0) ? qf0[s] : *(const bf16x8*)(Qs + r * AK_LD + 16 * s + 8 * hh);
;             st[mt] = (s == 0) ? MFMA32(a, qb_, zz) : MFMA32(a, qb_, st[mt]);
;           }
;       }
;       if (__builtin_amdgcn_ballot_w64(m[qs] != 0.f) != 0ull) {
; #pragma unroll
;         for (int i = 0; i < 16; ++i) { st[0][i] -= m[qs]; st[1][i] -= m[qs]; }
;       }
;       float mx = st[0][0];
; #pragma unroll
;       for (int i = 1; i < 16; ++i) mx = fmaxf(mx, st[0][i]);
; #pragma unroll
;       for (int i = 0; i < 16; ++i) mx = fmaxf(mx, st[1][i]);
;       mx = xhalf_max(mx);
;       if (__builtin_amdgcn_ballot_w64((kt == 0) ? (fabsf(mx) > 16.f) : (mx > 16.f)) != 0ull) {
;         const float d = (kt == 0) ? mx : fmaxf(mx, 0.f);
;         const float alpha = __builtin_amdgcn_exp2f(-d);
;         m[qs] += d; lsum[qs] *= alpha;
; #pragma unroll
;         for (int i = 0; i < 16; ++i) { ot[qs][0][i] *= alpha; ot[qs][1][i] *= alpha; st[0][i] -= d; st[1][i] -= d; }
;       }
;       float ps = 0.f;
; #pragma unroll
;       for (int sp = 0; sp < 4; ++sp) {
;         const int mt = sp >> 1, s2 = sp & 1;
;         float e[8];
; #pragma unroll
;         for (int j = 0; j < 8; ++j) { e[j] = __builtin_amdgcn_exp2f(st[mt][8 * s2 + j]); ps += e[j]; }
;         u32x4 pk;
;         pk[0] = pk2(e[0], e[1]); pk[1] = pk2(e[2], e[3]); pk[2] = pk2(e[4], e[5]); pk[3] = pk2(e[6], e[7]);
;         const bf16x8 pf = __builtin_bit_cast(bf16x8, pk);
; #pragma unroll
;         for (int vt = 0; vt < 2; ++vt) {
.Lattn_00_A_back:
	ds_read_b64 v[12:13], v202 offset:13344
	ds_read_b64 v[14:15], v202 offset:13360
	v_mfma_f32_32x32x16_bf16 v[16:31], v[192:195], v[104:107], v[16:31]
	v_exp_f32_e32 v80, v80
	v_exp_f32_e32 v81, v81
	v_exp_f32_e32 v82, v82
	ds_read_b64 v[192:193], v202 offset:17696
	ds_read_b64 v[194:195], v202 offset:17712
	v_mfma_f32_32x32x16_bf16 v[96:111], v[204:207], v[228:231], 0
	v_exp_f32_e32 v83, v83
	v_exp_f32_e32 v84, v84
	v_exp_f32_e32 v85, v85
	ds_read_b128 v[204:207], v159 offset:6656
	v_mfma_f32_32x32x16_bf16 v[96:111], v[208:211], v[232:235], v[96:111]
	v_exp_f32_e32 v86, v86
	v_exp_f32_e32 v87, v87
	v_add_f32_e32 v0, v0, v80
	v_add_f32_e32 v0, v0, v81
	ds_read_b128 v[208:211], v159 offset:6688
	v_mfma_f32_32x32x16_bf16 v[96:111], v[212:215], v[236:239], v[96:111]
	v_add_f32_e32 v0, v0, v82
	v_add_f32_e32 v0, v0, v83
	v_add_f32_e32 v0, v0, v84
	v_add_f32_e32 v0, v0, v85
	v_add_f32_e32 v0, v0, v86
	v_add_f32_e32 v0, v0, v87
	ds_read_b128 v[212:215], v159 offset:6720
	v_mfma_f32_32x32x16_bf16 v[96:111], v[216:219], v[240:243], v[96:111]
	v_cvt_pk_bf16_f32 v80, v80, v81
	v_cvt_pk_bf16_f32 v81, v82, v83
	v_cvt_pk_bf16_f32 v82, v84, v85
	v_cvt_pk_bf16_f32 v83, v86, v87
	v_exp_f32_e32 v88, v88
	ds_read_b128 v[216:219], v159 offset:6752
	v_mfma_f32_32x32x16_bf16 v[96:111], v[220:223], v[244:247], v[96:111]
	v_exp_f32_e32 v89, v89
	v_exp_f32_e32 v90, v90
	v_exp_f32_e32 v91, v91
	ds_read_b128 v[220:223], v159 offset:6784
	v_mfma_f32_32x32x16_bf16 v[96:111], v[224:227], v[248:251], v[96:111]
	v_exp_f32_e32 v92, v92
	v_exp_f32_e32 v93, v93
	v_exp_f32_e32 v94, v94
	ds_read_b128 v[224:227], v159 offset:6816
	s_waitcnt lgkmcnt(12)
	v_mfma_f32_32x32x16_bf16 v[64:79], v[4:7], v[80:83], v[64:79]
	v_exp_f32_e32 v95, v95
	v_add_f32_e32 v0, v0, v88
	v_add_f32_e32 v0, v0, v89
	v_add_f32_e32 v0, v0, v90
	v_add_f32_e32 v0, v0, v91
	s_waitcnt lgkmcnt(10)
	v_mfma_f32_32x32x16_bf16 v[48:63], v[8:11], v[80:83], v[48:63]
	v_add_f32_e32 v0, v0, v92
	v_add_f32_e32 v0, v0, v93
	v_add_f32_e32 v0, v0, v94
	v_add_f32_e32 v0, v0, v95
	v_cvt_pk_bf16_f32 v88, v88, v89
	v_cvt_pk_bf16_f32 v89, v90, v91
	s_waitcnt lgkmcnt(8)
	v_cvt_pk_bf16_f32 v90, v92, v93
	v_cvt_pk_bf16_f32 v91, v94, v95
	s_nop 1
	v_mfma_f32_32x32x16_bf16 v[64:79], v[12:15], v[88:91], v[64:79]
	s_cmp_eq_u32 s12, 0
	s_cbranch_scc1 .Lattn_00_B_nosub
	v_sub_f32_e32 v96, v96, v201
	v_sub_f32_e32 v97, v97, v201
	v_sub_f32_e32 v98, v98, v201
	v_sub_f32_e32 v99, v99, v201
	v_sub_f32_e32 v100, v100, v201
	v_sub_f32_e32 v101, v101, v201
	v_sub_f32_e32 v102, v102, v201
	v_sub_f32_e32 v103, v103, v201
	v_sub_f32_e32 v104, v104, v201
	v_sub_f32_e32 v105, v105, v201
	v_sub_f32_e32 v106, v106, v201
	v_sub_f32_e32 v107, v107, v201
	v_sub_f32_e32 v108, v108, v201
	v_sub_f32_e32 v109, v109, v201
	v_sub_f32_e32 v110, v110, v201
	v_sub_f32_e32 v111, v111, v201
.Lattn_00_B_nosub:
	v_max3_f32 v185, v96, v97, v98
	v_max3_f32 v185, v185, v99, v100
	v_max3_f32 v185, v185, v101, v102
	v_max3_f32 v185, v185, v103, v104
	v_max3_f32 v185, v185, v105, v106
	s_waitcnt lgkmcnt(6)
	v_mfma_f32_32x32x16_bf16 v[48:63], v[192:195], v[88:91], v[48:63]
	v_max3_f32 v185, v185, v107, v108
	v_max3_f32 v185, v185, v109, v110
	v_max_f32_e32 v185, v185, v111
	v_cndmask_b32_e64 v191, v185, |v185|, s[4:5]
	v_cmp_lt_f32_e32 vcc, s33, v191
	s_cbranch_vccnz .Lattn_00_B_rare
.Lattn_00_B_back:
	s_waitcnt lgkmcnt(5)
	v_mfma_f32_32x32x16_bf16 v[80:95], v[204:207], v[112:115], 0
	v_exp_f32_e32 v96, v96
	v_exp_f32_e32 v97, v97
	v_exp_f32_e32 v98, v98
	s_waitcnt vmcnt(0)
	ds_write_b128 v3, v[136:139] offset:22016
	s_waitcnt lgkmcnt(5)
	v_mfma_f32_32x32x16_bf16 v[80:95], v[208:211], v[116:119], v[80:95]
	v_exp_f32_e32 v99, v99
	v_exp_f32_e32 v100, v100
	v_exp_f32_e32 v101, v101
	ds_write_b128 v161, v[140:143] offset:22016
	s_waitcnt lgkmcnt(5)
	v_mfma_f32_32x32x16_bf16 v[80:95], v[212:215], v[120:123], v[80:95]
	v_exp_f32_e32 v102, v102
	v_exp_f32_e32 v103, v103
	v_add_f32_e32 v203, v203, v96
	v_add_f32_e32 v203, v203, v97
	ds_write_b128 v182, v[144:147] offset:22016
	s_waitcnt lgkmcnt(5)
	v_mfma_f32_32x32x16_bf16 v[80:95], v[216:219], v[124:127], v[80:95]
	v_add_f32_e32 v203, v203, v98
	v_add_f32_e32 v203, v203, v99
	v_add_f32_e32 v203, v203, v100
	v_add_f32_e32 v203, v203, v101
	v_add_f32_e32 v203, v203, v102
	v_add_f32_e32 v203, v203, v103
	ds_write_b64 v184, v[148:149] offset:35328
	ds_write_b64 v184, v[150:151] offset:35336
	s_waitcnt lgkmcnt(6)
	v_mfma_f32_32x32x16_bf16 v[80:95], v[220:223], v[128:131], v[80:95]
	v_cvt_pk_bf16_f32 v96, v96, v97
	v_cvt_pk_bf16_f32 v97, v98, v99
	v_cvt_pk_bf16_f32 v98, v100, v101
	v_cvt_pk_bf16_f32 v99, v102, v103
	v_exp_f32_e32 v104, v104
	ds_write_b64 v184, v[152:153] offset:39680
	ds_write_b64 v184, v[154:155] offset:39688
	s_waitcnt lgkmcnt(7)
	v_mfma_f32_32x32x16_bf16 v[80:95], v[224:227], v[132:135], v[80:95]
	v_exp_f32_e32 v105, v105
	v_exp_f32_e32 v106, v106
	v_exp_f32_e32 v107, v107
	global_load_dwordx4 v[136:139], v166, s[10:11]
	global_load_dwordx4 v[140:143], v168, s[10:11]
	global_load_dwordx4 v[144:147], v170, s[10:11]
	global_load_dwordx4 v[148:151], v162, s[2:3]
	global_load_dwordx4 v[152:155], v164, s[2:3]
	s_add_u32 s10, s10, 0x3000
	s_addc_u32 s11, s11, 0
	s_add_u32 s2, s2, 0x80
	s_addc_u32 s3, s3, 0
	s_waitcnt lgkmcnt(0)
	s_barrier
	v_mfma_f32_32x32x16_bf16 v[32:47], v[4:7], v[96:99], v[32:47]
	v_exp_f32_e32 v108, v108
	v_exp_f32_e32 v109, v109
	v_exp_f32_e32 v110, v110
	ds_read_b64 v[4:5], v202 offset:13376
	ds_read_b64 v[6:7], v202 offset:13392
	v_mfma_f32_32x32x16_bf16 v[16:31], v[8:11], v[96:99], v[16:31]
	v_exp_f32_e32 v111, v111
	v_add_f32_e32 v203, v203, v104
	v_add_f32_e32 v203, v203, v105
	v_add_f32_e32 v203, v203, v106
	v_add_f32_e32 v203, v203, v107
	ds_read_b64 v[8:9], v202 offset:17728
	ds_read_b64 v[10:11], v202 offset:17744
	v_add_f32_e32 v203, v203, v108
	v_add_f32_e32 v203, v203, v109
	v_add_f32_e32 v203, v203, v110
	v_add_f32_e32 v203, v203, v111
	v_cvt_pk_bf16_f32 v104, v104, v105
	v_cvt_pk_bf16_f32 v105, v106, v107
	v_cvt_pk_bf16_f32 v106, v108, v109
	v_cvt_pk_bf16_f32 v107, v110, v111
	s_nop 1
	v_mfma_f32_32x32x16_bf16 v[32:47], v[12:15], v[104:107], v[32:47]
	s_cmp_eq_u32 s9, 0
	s_cbranch_scc1 .Lattn_01_A_nosub
	v_sub_f32_e32 v80, v80, v2
	v_sub_f32_e32 v81, v81, v2
	v_sub_f32_e32 v82, v82, v2
	v_sub_f32_e32 v83, v83, v2
	v_sub_f32_e32 v84, v84, v2
	v_sub_f32_e32 v85, v85, v2
	v_sub_f32_e32 v86, v86, v2
	v_sub_f32_e32 v87, v87, v2
	v_sub_f32_e32 v88, v88, v2
	v_sub_f32_e32 v89, v89, v2
	v_sub_f32_e32 v90, v90, v2
	v_sub_f32_e32 v91, v91, v2
	v_sub_f32_e32 v92, v92, v2
	v_sub_f32_e32 v93, v93, v2
	v_sub_f32_e32 v94, v94, v2
	v_sub_f32_e32 v95, v95, v2

; #define MFMA32(a, b, c) __builtin_amdgcn_mfma_f32_32x32x16_bf16((a), (b), (c), 0, 0, 0)
; DI void attn_item(const Ctx& c, int item, bf16* lds) {
;     ...
;         for (int mt = 0; mt < 2; ++mt)
; #pragma unroll
;           for (int s = 0; s < 6; ++s) {
;             const bf16x8 a = *(const bf16x8*)(Ks + (32 * mt + r) * AK_LD + 16 * s + 8 * hh);
;             const bf16x8 qb_ = (qs == 0) ? qf0[s] : *(const bf16x8*)(Qs + r * AK_LD + 16 * s + 8 * hh);
;             st[mt] = (s == 0) ? MFMA32(a, qb_, zz) : MFMA32(a, qb_, st[mt]);
;           }
;       }
;       if (__builtin_amdgcn_ballot_w64(m[qs] != 0.f) != 0ull) {
; #pragma unroll
;         for (int i = 0; i < 16; ++i) { st[0][i] -= m[qs]; st[1][i] -= m[qs]; }
;       }
;       float mx = st[0][0];
; #pragma unroll
;       for (int i = 1; i < 16; ++i) mx = fmaxf(mx, st[0][i]);
; #pragma unroll
;       for (int i = 0; i < 16; ++i) mx = fmaxf(mx, st[1][i]);
;       mx = xhalf_max(mx);
;       if (__builtin_amdgcn_ballot_w64((kt == 0) ? (fabsf(mx) > 16.f) : (mx > 16.f)) != 0ull) {
;         const float d = (kt == 0) ? mx : fmaxf(mx, 0.f);
;         const float alpha = __builtin_amdgcn_exp2f(-d);
;         m[qs] += d; lsum[qs] *= alpha;
; #pragma unroll
;         for (int i = 0; i < 16; ++i) { ot[qs][0][i] *= alpha; ot[qs][1][i] *= alpha; st[0][i] -= d; st[1][i] -= d; }
;       }
;       float ps = 0.f;
; #pragma unroll
;       for (int sp = 0; sp < 4; ++sp) {
;         const int mt = sp >> 1, s2 = sp & 1;
;         float e[8];
; #pragma unroll
;         for (int j = 0; j < 8; ++j) { e[j] = __builtin_amdgcn_exp2f(st[mt][8 * s2 + j]); ps += e[j]; }
;         u32x4 pk;
;         pk[0] = pk2(e[0], e[1]); pk[1] = pk2(e[2], e[3]); pk[2] = pk2(e[4], e[5]); pk[3] = pk2(e[6], e[7]);
;         const bf16x8 pf = __builtin_bit_cast(bf16x8, pk);
; #pragma unroll
;         for (int vt = 0; vt < 2; ++vt) {
;           const bf16* vp = Vs + (32 * vt + r) * AV_LD + 32 * mt + 16 * s2 + 4 * hh;
;           const s16x4 lo = *(const s16x4*)(vp), hi = *(const s16x4*)(vp + 8);
;           const bf16x8 a = __builtin_shufflevector(lo, hi, 0, 1, 2, 3, 4, 5, 6, 7);
;           ot[qs][vt] = MFMA32(a, pf, ot[qs][vt]);
.Lattn_10_A_back:
	ds_read_b64 v[192:193], v202 offset:39712
	ds_read_b64 v[194:195], v202 offset:39728
	v_mfma_f32_32x32x16_bf16 v[96:111], v[204:207], v[228:231], 0
	v_exp_f32_e32 v80, v80
	v_exp_f32_e32 v81, v81
	v_exp_f32_e32 v82, v82
	ds_read_b128 v[204:207], v159 offset:28672
	v_mfma_f32_32x32x16_bf16 v[96:111], v[208:211], v[232:235], v[96:111]
	v_exp_f32_e32 v83, v83
	v_exp_f32_e32 v84, v84
	v_exp_f32_e32 v85, v85
	ds_read_b128 v[208:211], v159 offset:28704
	v_mfma_f32_32x32x16_bf16 v[96:111], v[212:215], v[236:239], v[96:111]
	v_exp_f32_e32 v86, v86
	v_exp_f32_e32 v87, v87
	v_add_f32_e32 v0, v0, v80
	v_add_f32_e32 v0, v0, v81
	ds_read_b128 v[212:215], v159 offset:28736
	v_mfma_f32_32x32x16_bf16 v[96:111], v[216:219], v[240:243], v[96:111]
	v_add_f32_e32 v0, v0, v82
	v_add_f32_e32 v0, v0, v83
	v_add_f32_e32 v0, v0, v84
	v_add_f32_e32 v0, v0, v85
	v_add_f32_e32 v0, v0, v86
	v_add_f32_e32 v0, v0, v87
	ds_read_b128 v[216:219], v159 offset:28768
	v_mfma_f32_32x32x16_bf16 v[96:111], v[220:223], v[244:247], v[96:111]
	v_cvt_pk_bf16_f32 v80, v80, v81
	v_cvt_pk_bf16_f32 v81, v82, v83
	v_cvt_pk_bf16_f32 v82, v84, v85
	v_cvt_pk_bf16_f32 v83, v86, v87
	v_exp_f32_e32 v88, v88
	ds_read_b128 v[220:223], v159 offset:28800
	v_mfma_f32_32x32x16_bf16 v[96:111], v[224:227], v[248:251], v[96:111]
	v_exp_f32_e32 v89, v89
	v_exp_f32_e32 v90, v90
	v_exp_f32_e32 v91, v91
	ds_read_b128 v[224:227], v159 offset:28832
	s_waitcnt lgkmcnt(12)
	v_mfma_f32_32x32x16_bf16 v[64:79], v[4:7], v[80:83], v[64:79]
	v_exp_f32_e32 v92, v92
	v_exp_f32_e32 v93, v93
	v_exp_f32_e32 v94, v94
	s_waitcnt lgkmcnt(10)
	v_mfma_f32_32x32x16_bf16 v[48:63], v[8:11], v[80:83], v[48:63]
	v_exp_f32_e32 v95, v95
	v_add_f32_e32 v0, v0, v88
	v_add_f32_e32 v0, v0, v89
	v_add_f32_e32 v0, v0, v90
	v_add_f32_e32 v0, v0, v91
	s_waitcnt lgkmcnt(8)
	v_add_f32_e32 v0, v0, v92
	v_add_f32_e32 v0, v0, v93
	v_add_f32_e32 v0, v0, v94
	v_add_f32_e32 v0, v0, v95
	v_cvt_pk_bf16_f32 v88, v88, v89
	v_cvt_pk_bf16_f32 v89, v90, v91
	v_cvt_pk_bf16_f32 v90, v92, v93
	v_cvt_pk_bf16_f32 v91, v94, v95
	s_nop 1
	v_mfma_f32_32x32x16_bf16 v[64:79], v[12:15], v[88:91], v[64:79]
	s_cmp_eq_u32 s12, 0
	s_cbranch_scc1 .Lattn_10_B_nosub
	v_sub_f32_e32 v96, v96, v201
	v_sub_f32_e32 v97, v97, v201
	v_sub_f32_e32 v98, v98, v201
	v_sub_f32_e32 v99, v99, v201
	v_sub_f32_e32 v100, v100, v201
	v_sub_f32_e32 v101, v101, v201
	v_sub_f32_e32 v102, v102, v201
	v_sub_f32_e32 v103, v103, v201
	v_sub_f32_e32 v104, v104, v201
	v_sub_f32_e32 v105, v105, v201
	v_sub_f32_e32 v106, v106, v201
	v_sub_f32_e32 v107, v107, v201
	v_sub_f32_e32 v108, v108, v201
	v_sub_f32_e32 v109, v109, v201
	v_sub_f32_e32 v110, v110, v201
	v_sub_f32_e32 v111, v111, v201

; #define MFMA32(a, b, c) __builtin_amdgcn_mfma_f32_32x32x16_bf16((a), (b), (c), 0, 0, 0)
; DI void attn_item(const Ctx& c, int item, bf16* lds) {
;     ...
;     if (kt + 1 < ntile) {
;       const bf16* kn = Kb + (size_t)(kt + 1) * 64 * 96;
;       const bf16* vn = Vb + (kt + 1) * 64;
; #pragma unroll
;       for (int i = 0; i < 3; ++i) rk[i] = *(const u32x4*)(kn + (koff + 2048u * i));
; #pragma unroll
;       for (int i = 0; i < 2; ++i) rv[i] = *(const u32x4*)(vn + (voff + (unsigned)(32 * T) * i));
;     }
; #pragma unroll
;     for (int qs = 0; qs < 2; ++qs) {
;       __builtin_amdgcn_sched_barrier(0);
;       f32x16 st[2];
;       {
;         f32x16 zz;
; #pragma unroll
;         for (int i = 0; i < 16; ++i) zz[i] = 0.f;
; #pragma unroll
;         for (int mt = 0; mt < 2; ++mt)
; #pragma unroll
;           for (int s = 0; s < 6; ++s) {
;             const bf16x8 a = *(const bf16x8*)(Ks + (32 * mt + r) * AK_LD + 16 * s + 8 * hh);
;             const bf16x8 qb_ = (qs == 0) ? qf0[s] : *(const bf16x8*)(Qs + r * AK_LD + 16 * s + 8 * hh);
;             st[mt] = (s == 0) ? MFMA32(a, qb_, zz) : MFMA32(a, qb_, st[mt]);
;           }
;       }
;       if (__builtin_amdgcn_ballot_w64(m[qs] != 0.f) != 0ull) {
; #pragma unroll
;         for (int i = 0; i < 16; ++i) { st[0][i] -= m[qs]; st[1][i] -= m[qs]; }
;       }
;       float mx = st[0][0];
; #pragma unroll
;       for (int i = 1; i < 16; ++i) mx = fmaxf(mx, st[0][i]);
; #pragma unroll
;       for (int i = 0; i < 16; ++i) mx = fmaxf(mx, st[1][i]);
;       mx = xhalf_max(mx);
;       if (__builtin_amdgcn_ballot_w64((kt == 0) ? (fabsf(mx) > 16.f) : (mx > 16.f)) != 0ull) {
;         const float d = (kt == 0) ? mx : fmaxf(mx, 0.f);
;         const float alpha = __builtin_amdgcn_exp2f(-d);
;         m[qs] += d; lsum[qs] *= alpha;
; #pragma unroll
;         for (int i = 0; i < 16; ++i) { ot[qs][0][i] *= alpha; ot[qs][1][i] *= alpha; st[0][i] -= d; st[1][i] -= d; }
;       }
;       float ps = 0.f;
; #pragma unroll
;       for (int sp = 0; sp < 4; ++sp) {
;         const int mt = sp >> 1, s2 = sp & 1;
;         float e[8];
; #pragma unroll
;         for (int j = 0; j < 8; ++j) { e[j] = __builtin_amdgcn_exp2f(st[mt][8 * s2 + j]); ps += e[j]; }
.Lattn_10_B_back:
	s_waitcnt lgkmcnt(5)
	v_mfma_f32_32x32x16_bf16 v[80:95], v[204:207], v[112:115], 0
	v_exp_f32_e32 v96, v96
	v_exp_f32_e32 v97, v97
	v_exp_f32_e32 v98, v98
	s_waitcnt vmcnt(0)
	ds_write_b128 v3, v[136:139] offset:44032
	s_waitcnt lgkmcnt(5)
	v_mfma_f32_32x32x16_bf16 v[80:95], v[208:211], v[116:119], v[80:95]
	v_exp_f32_e32 v99, v99
	v_exp_f32_e32 v100, v100
	v_exp_f32_e32 v101, v101
	ds_write_b128 v161, v[140:143] offset:44032
	s_waitcnt lgkmcnt(5)
	v_mfma_f32_32x32x16_bf16 v[80:95], v[212:215], v[120:123], v[80:95]
	v_exp_f32_e32 v102, v102
	v_exp_f32_e32 v103, v103
	v_add_f32_e32 v203, v203, v96
	v_add_f32_e32 v203, v203, v97
	ds_write_b128 v182, v[144:147] offset:44032
	s_waitcnt lgkmcnt(5)
	v_mfma_f32_32x32x16_bf16 v[80:95], v[216:219], v[124:127], v[80:95]
	v_add_f32_e32 v203, v203, v98
	v_add_f32_e32 v203, v203, v99
	v_add_f32_e32 v203, v203, v100
	v_add_f32_e32 v203, v203, v101
	v_add_f32_e32 v203, v203, v102
	v_add_f32_e32 v203, v203, v103
	ds_write_b64 v184, v[148:149] offset:57344
	ds_write_b64 v184, v[150:151] offset:57352
	s_waitcnt lgkmcnt(6)
	v_mfma_f32_32x32x16_bf16 v[80:95], v[220:223], v[128:131], v[80:95]
	v_cvt_pk_bf16_f32 v96, v96, v97
	v_cvt_pk_bf16_f32 v97, v98, v99
	v_cvt_pk_bf16_f32 v98, v100, v101
	v_cvt_pk_bf16_f32 v99, v102, v103
	v_exp_f32_e32 v104, v104
	ds_write_b64 v184, v[152:153] offset:61696
	ds_write_b64 v184, v[154:155] offset:61704
	s_waitcnt lgkmcnt(7)
	v_mfma_f32_32x32x16_bf16 v[80:95], v[224:227], v[132:135], v[80:95]
	v_exp_f32_e32 v105, v105
	v_exp_f32_e32 v106, v106
	v_exp_f32_e32 v107, v107
	global_load_dwordx4 v[136:139], v166, s[10:11]
	global_load_dwordx4 v[140:143], v168, s[10:11]
	global_load_dwordx4 v[144:147], v170, s[10:11]
	global_load_dwordx4 v[148:151], v162, s[2:3]
	global_load_dwordx4 v[152:155], v164, s[2:3]
	s_add_u32 s10, s10, 0x3000
	s_addc_u32 s11, s11, 0
	s_add_u32 s2, s2, 0x80
	s_addc_u32 s3, s3, 0
	s_waitcnt lgkmcnt(0)
	s_barrier
	v_mfma_f32_32x32x16_bf16 v[32:47], v[4:7], v[96:99], v[32:47]
	v_exp_f32_e32 v108, v108
	v_exp_f32_e32 v109, v109
	v_exp_f32_e32 v110, v110
	ds_read_b64 v[4:5], v202 offset:35392
	ds_read_b64 v[6:7], v202 offset:35408
	v_mfma_f32_32x32x16_bf16 v[16:31], v[8:11], v[96:99], v[16:31]
	v_exp_f32_e32 v111, v111
	v_add_f32_e32 v203, v203, v104
	v_add_f32_e32 v203, v203, v105
	v_add_f32_e32 v203, v203, v106
	v_add_f32_e32 v203, v203, v107
	ds_read_b64 v[8:9], v202 offset:39744
	ds_read_b64 v[10:11], v202 offset:39760
	v_add_f32_e32 v203, v203, v108
	v_add_f32_e32 v203, v203, v109
	v_add_f32_e32 v203, v203, v110
	v_add_f32_e32 v203, v203, v111
	v_cvt_pk_bf16_f32 v104, v104, v105
	v_cvt_pk_bf16_f32 v105, v106, v107
	v_cvt_pk_bf16_f32 v106, v108, v109
	v_cvt_pk_bf16_f32 v107, v110, v111
	s_nop 1
	v_mfma_f32_32x32x16_bf16 v[32:47], v[12:15], v[104:107], v[32:47]
	s_cmp_eq_u32 s9, 0
	s_cbranch_scc1 .Lattn_11_A_nosub
	v_sub_f32_e32 v80, v80, v2
	v_sub_f32_e32 v81, v81, v2
	v_sub_f32_e32 v82, v82, v2
	v_sub_f32_e32 v83, v83, v2
	v_sub_f32_e32 v84, v84, v2
	v_sub_f32_e32 v85, v85, v2
	v_sub_f32_e32 v86, v86, v2
	v_sub_f32_e32 v87, v87, v2
	v_sub_f32_e32 v88, v88, v2
	v_sub_f32_e32 v89, v89, v2
	v_sub_f32_e32 v90, v90, v2
	v_sub_f32_e32 v91, v91, v2
	v_sub_f32_e32 v92, v92, v2
	v_sub_f32_e32 v93, v93, v2
	v_sub_f32_e32 v94, v94, v2
	v_sub_f32_e32 v95, v95, v2

; #define MFMA32(a, b, c) __builtin_amdgcn_mfma_f32_32x32x16_bf16((a), (b), (c), 0, 0, 0)
; DI void attn_item(const Ctx& c, int item, bf16* lds) {
;     ...
;         for (int mt = 0; mt < 2; ++mt)
; #pragma unroll
;           for (int s = 0; s < 6; ++s) {
;             const bf16x8 a = *(const bf16x8*)(Ks + (32 * mt + r) * AK_LD + 16 * s + 8 * hh);
;             const bf16x8 qb_ = (qs == 0) ? qf0[s] : *(const bf16x8*)(Qs + r * AK_LD + 16 * s + 8 * hh);
;             st[mt] = (s == 0) ? MFMA32(a, qb_, zz) : MFMA32(a, qb_, st[mt]);
;           }
;       }
;       if (__builtin_amdgcn_ballot_w64(m[qs] != 0.f) != 0ull) {
; #pragma unroll
;         for (int i = 0; i < 16; ++i) { st[0][i] -= m[qs]; st[1][i] -= m[qs]; }
;       }
;       float mx = st[0][0];
; #pragma unroll
;       for (int i = 1; i < 16; ++i) mx = fmaxf(mx, st[0][i]);
; #pragma unroll
;       for (int i = 0; i < 16; ++i) mx = fmaxf(mx, st[1][i]);
;       mx = xhalf_max(mx);
;       if (__builtin_amdgcn_ballot_w64((kt == 0) ? (fabsf(mx) > 16.f) : (mx > 16.f)) != 0ull) {
;         const float d = (kt == 0) ? mx : fmaxf(mx, 0.f);
;         const float alpha = __builtin_amdgcn_exp2f(-d);
;         m[qs] += d; lsum[qs] *= alpha;
; #pragma unroll
;         for (int i = 0; i < 16; ++i) { ot[qs][0][i] *= alpha; ot[qs][1][i] *= alpha; st[0][i] -= d; st[1][i] -= d; }
;       }
;       float ps = 0.f;
; #pragma unroll
;       for (int sp = 0; sp < 4; ++sp) {
;         const int mt = sp >> 1, s2 = sp & 1;
;         float e[8];
; #pragma unroll
;         for (int j = 0; j < 8; ++j) { e[j] = __builtin_amdgcn_exp2f(st[mt][8 * s2 + j]); ps += e[j]; }
;         u32x4 pk;
;         pk[0] = pk2(e[0], e[1]); pk[1] = pk2(e[2], e[3]); pk[2] = pk2(e[4], e[5]); pk[3] = pk2(e[6], e[7]);
;         const bf16x8 pf = __builtin_bit_cast(bf16x8, pk);
; #pragma unroll
;         for (int vt = 0; vt < 2; ++vt) {
;           const bf16* vp = Vs + (32 * vt + r) * AV_LD + 32 * mt + 16 * s2 + 4 * hh;
;           const s16x4 lo = *(const s16x4*)(vp), hi = *(const s16x4*)(vp + 8);
;           const bf16x8 a = __builtin_shufflevector(lo, hi, 0, 1, 2, 3, 4, 5, 6, 7);
;           ot[qs][vt] = MFMA32(a, pf, ot[qs][vt]);
.Lattn_20_A_back:
	ds_read_b64 v[192:193], v202 offset:61728
	ds_read_b64 v[194:195], v202 offset:61744
	v_mfma_f32_32x32x16_bf16 v[96:111], v[204:207], v[228:231], 0
	v_exp_f32_e32 v80, v80
	v_exp_f32_e32 v81, v81
	v_exp_f32_e32 v82, v82
	ds_read_b128 v[204:207], v159 offset:50688
	v_mfma_f32_32x32x16_bf16 v[96:111], v[208:211], v[232:235], v[96:111]
	v_exp_f32_e32 v83, v83
	v_exp_f32_e32 v84, v84
	v_exp_f32_e32 v85, v85
	ds_read_b128 v[208:211], v159 offset:50720
	v_mfma_f32_32x32x16_bf16 v[96:111], v[212:215], v[236:239], v[96:111]
	v_exp_f32_e32 v86, v86
	v_exp_f32_e32 v87, v87
	v_add_f32_e32 v0, v0, v80
	v_add_f32_e32 v0, v0, v81
	ds_read_b128 v[212:215], v159 offset:50752
	v_mfma_f32_32x32x16_bf16 v[96:111], v[216:219], v[240:243], v[96:111]
	v_add_f32_e32 v0, v0, v82
	v_add_f32_e32 v0, v0, v83
	v_add_f32_e32 v0, v0, v84
	v_add_f32_e32 v0, v0, v85
	v_add_f32_e32 v0, v0, v86
	v_add_f32_e32 v0, v0, v87
	ds_read_b128 v[216:219], v159 offset:50784
	v_mfma_f32_32x32x16_bf16 v[96:111], v[220:223], v[244:247], v[96:111]
	v_cvt_pk_bf16_f32 v80, v80, v81
	v_cvt_pk_bf16_f32 v81, v82, v83
	v_cvt_pk_bf16_f32 v82, v84, v85
	v_cvt_pk_bf16_f32 v83, v86, v87
	v_exp_f32_e32 v88, v88
	ds_read_b128 v[220:223], v159 offset:50816
	v_mfma_f32_32x32x16_bf16 v[96:111], v[224:227], v[248:251], v[96:111]
	v_exp_f32_e32 v89, v89
	v_exp_f32_e32 v90, v90
	v_exp_f32_e32 v91, v91
	ds_read_b128 v[224:227], v159 offset:50848
	s_waitcnt lgkmcnt(12)
	v_mfma_f32_32x32x16_bf16 v[64:79], v[4:7], v[80:83], v[64:79]
	v_exp_f32_e32 v92, v92
	v_exp_f32_e32 v93, v93
	v_exp_f32_e32 v94, v94
	s_waitcnt lgkmcnt(10)
	v_mfma_f32_32x32x16_bf16 v[48:63], v[8:11], v[80:83], v[48:63]
	v_exp_f32_e32 v95, v95
	v_add_f32_e32 v0, v0, v88
	v_add_f32_e32 v0, v0, v89
	v_add_f32_e32 v0, v0, v90
	v_add_f32_e32 v0, v0, v91
	s_waitcnt lgkmcnt(8)
	v_add_f32_e32 v0, v0, v92
	v_add_f32_e32 v0, v0, v93
	v_add_f32_e32 v0, v0, v94
	v_add_f32_e32 v0, v0, v95
	v_cvt_pk_bf16_f32 v88, v88, v89
	v_cvt_pk_bf16_f32 v89, v90, v91
	v_cvt_pk_bf16_f32 v90, v92, v93
	v_cvt_pk_bf16_f32 v91, v94, v95
	s_nop 1
	v_mfma_f32_32x32x16_bf16 v[64:79], v[12:15], v[88:91], v[64:79]
	s_cmp_eq_u32 s12, 0
	s_cbranch_scc1 .Lattn_20_B_nosub
	v_sub_f32_e32 v96, v96, v201
	v_sub_f32_e32 v97, v97, v201
	v_sub_f32_e32 v98, v98, v201
	v_sub_f32_e32 v99, v99, v201
	v_sub_f32_e32 v100, v100, v201
	v_sub_f32_e32 v101, v101, v201
	v_sub_f32_e32 v102, v102, v201
	v_sub_f32_e32 v103, v103, v201
	v_sub_f32_e32 v104, v104, v201
	v_sub_f32_e32 v105, v105, v201
	v_sub_f32_e32 v106, v106, v201
	v_sub_f32_e32 v107, v107, v201
	v_sub_f32_e32 v108, v108, v201
	v_sub_f32_e32 v109, v109, v201
	v_sub_f32_e32 v110, v110, v201
	v_sub_f32_e32 v111, v111, v201

; #define MFMA32(a, b, c) __builtin_amdgcn_mfma_f32_32x32x16_bf16((a), (b), (c), 0, 0, 0)
; DI void attn_item(const Ctx& c, int item, bf16* lds) {
;     ...
;     if (kt + 1 < ntile) {
;       const bf16* kn = Kb + (size_t)(kt + 1) * 64 * 96;
;       const bf16* vn = Vb + (kt + 1) * 64;
; #pragma unroll
;       for (int i = 0; i < 3; ++i) rk[i] = *(const u32x4*)(kn + (koff + 2048u * i));
; #pragma unroll
;       for (int i = 0; i < 2; ++i) rv[i] = *(const u32x4*)(vn + (voff + (unsigned)(32 * T) * i));
;     }
; #pragma unroll
;     for (int qs = 0; qs < 2; ++qs) {
;       __builtin_amdgcn_sched_barrier(0);
;       f32x16 st[2];
;       {
;         f32x16 zz;
; #pragma unroll
;         for (int i = 0; i < 16; ++i) zz[i] = 0.f;
; #pragma unroll
;         for (int mt = 0; mt < 2; ++mt)
; #pragma unroll
;           for (int s = 0; s < 6; ++s) {
;             const bf16x8 a = *(const bf16x8*)(Ks + (32 * mt + r) * AK_LD + 16 * s + 8 * hh);
;             const bf16x8 qb_ = (qs == 0) ? qf0[s] : *(const bf16x8*)(Qs + r * AK_LD + 16 * s + 8 * hh);
;             st[mt] = (s == 0) ? MFMA32(a, qb_, zz) : MFMA32(a, qb_, st[mt]);
;           }
;       }
;       if (__builtin_amdgcn_ballot_w64(m[qs] != 0.f) != 0ull) {
; #pragma unroll
;         for (int i = 0; i < 16; ++i) { st[0][i] -= m[qs]; st[1][i] -= m[qs]; }
;       }
;       float mx = st[0][0];
; #pragma unroll
;       for (int i = 1; i < 16; ++i) mx = fmaxf(mx, st[0][i]);
; #pragma unroll
;       for (int i = 0; i < 16; ++i) mx = fmaxf(mx, st[1][i]);
;       mx = xhalf_max(mx);
;       if (__builtin_amdgcn_ballot_w64((kt == 0) ? (fabsf(mx) > 16.f) : (mx > 16.f)) != 0ull) {
;         const float d = (kt == 0) ? mx : fmaxf(mx, 0.f);
;         const float alpha = __builtin_amdgcn_exp2f(-d);
;         m[qs] += d; lsum[qs] *= alpha;
; #pragma unroll
;         for (int i = 0; i < 16; ++i) { ot[qs][0][i] *= alpha; ot[qs][1][i] *= alpha; st[0][i] -= d; st[1][i] -= d; }
;       }
;       float ps = 0.f;
; #pragma unroll
;       for (int sp = 0; sp < 4; ++sp) {
;         const int mt = sp >> 1, s2 = sp & 1;
;         float e[8];
; #pragma unroll
;         for (int j = 0; j < 8; ++j) { e[j] = __builtin_amdgcn_exp2f(st[mt][8 * s2 + j]); ps += e[j]; }
.Lattn_20_B_back:
	s_waitcnt lgkmcnt(5)
	v_mfma_f32_32x32x16_bf16 v[80:95], v[204:207], v[112:115], 0
	v_exp_f32_e32 v96, v96
	v_exp_f32_e32 v97, v97
	v_exp_f32_e32 v98, v98
	s_waitcnt vmcnt(0)
	ds_write_b128 v3, v[136:139] offset:0
	s_waitcnt lgkmcnt(5)
	v_mfma_f32_32x32x16_bf16 v[80:95], v[208:211], v[116:119], v[80:95]
	v_exp_f32_e32 v99, v99
	v_exp_f32_e32 v100, v100
	v_exp_f32_e32 v101, v101
	ds_write_b128 v161, v[140:143] offset:0
	s_waitcnt lgkmcnt(5)
	v_mfma_f32_32x32x16_bf16 v[80:95], v[212:215], v[120:123], v[80:95]
	v_exp_f32_e32 v102, v102
	v_exp_f32_e32 v103, v103
	v_add_f32_e32 v203, v203, v96
	v_add_f32_e32 v203, v203, v97
	ds_write_b128 v182, v[144:147] offset:0
	s_waitcnt lgkmcnt(5)
	v_mfma_f32_32x32x16_bf16 v[80:95], v[216:219], v[124:127], v[80:95]
	v_add_f32_e32 v203, v203, v98
	v_add_f32_e32 v203, v203, v99
	v_add_f32_e32 v203, v203, v100
	v_add_f32_e32 v203, v203, v101
	v_add_f32_e32 v203, v203, v102
	v_add_f32_e32 v203, v203, v103
	ds_write_b64 v184, v[148:149] offset:13312
	ds_write_b64 v184, v[150:151] offset:13320
	s_waitcnt lgkmcnt(6)
	v_mfma_f32_32x32x16_bf16 v[80:95], v[220:223], v[128:131], v[80:95]
	v_cvt_pk_bf16_f32 v96, v96, v97
	v_cvt_pk_bf16_f32 v97, v98, v99
	v_cvt_pk_bf16_f32 v98, v100, v101
	v_cvt_pk_bf16_f32 v99, v102, v103
	v_exp_f32_e32 v104, v104
	ds_write_b64 v184, v[152:153] offset:17664
	ds_write_b64 v184, v[154:155] offset:17672
	s_waitcnt lgkmcnt(7)
	v_mfma_f32_32x32x16_bf16 v[80:95], v[224:227], v[132:135], v[80:95]
	v_exp_f32_e32 v105, v105
	v_exp_f32_e32 v106, v106
	v_exp_f32_e32 v107, v107
	global_load_dwordx4 v[136:139], v166, s[10:11]
	global_load_dwordx4 v[140:143], v168, s[10:11]
	global_load_dwordx4 v[144:147], v170, s[10:11]
	global_load_dwordx4 v[148:151], v162, s[2:3]
	global_load_dwordx4 v[152:155], v164, s[2:3]
	s_add_u32 s10, s10, 0x3000
	s_addc_u32 s11, s11, 0
	s_add_u32 s2, s2, 0x80
	s_addc_u32 s3, s3, 0
	s_waitcnt lgkmcnt(0)
	s_barrier
	v_mfma_f32_32x32x16_bf16 v[32:47], v[4:7], v[96:99], v[32:47]
	v_exp_f32_e32 v108, v108
	v_exp_f32_e32 v109, v109
	v_exp_f32_e32 v110, v110
	ds_read_b64 v[4:5], v202 offset:57408
	ds_read_b64 v[6:7], v202 offset:57424
	v_mfma_f32_32x32x16_bf16 v[16:31], v[8:11], v[96:99], v[16:31]
	v_exp_f32_e32 v111, v111
	v_add_f32_e32 v203, v203, v104
	v_add_f32_e32 v203, v203, v105
	v_add_f32_e32 v203, v203, v106
	v_add_f32_e32 v203, v203, v107
	ds_read_b64 v[8:9], v202 offset:61760
	ds_read_b64 v[10:11], v202 offset:61776
	v_add_f32_e32 v203, v203, v108
	v_add_f32_e32 v203, v203, v109
	v_add_f32_e32 v203, v203, v110
	v_add_f32_e32 v203, v203, v111
	v_cvt_pk_bf16_f32 v104, v104, v105
	v_cvt_pk_bf16_f32 v105, v106, v107
	v_cvt_pk_bf16_f32 v106, v108, v109
	v_cvt_pk_bf16_f32 v107, v110, v111
	s_nop 1
	v_mfma_f32_32x32x16_bf16 v[32:47], v[12:15], v[104:107], v[32:47]
	s_cmp_eq_u32 s9, 0
	s_cbranch_scc1 .Lattn_21_A_nosub
	v_sub_f32_e32 v80, v80, v2
	v_sub_f32_e32 v81, v81, v2
	v_sub_f32_e32 v82, v82, v2
	v_sub_f32_e32 v83, v83, v2
	v_sub_f32_e32 v84, v84, v2
	v_sub_f32_e32 v85, v85, v2
	v_sub_f32_e32 v86, v86, v2
	v_sub_f32_e32 v87, v87, v2
	v_sub_f32_e32 v88, v88, v2
	v_sub_f32_e32 v89, v89, v2
	v_sub_f32_e32 v90, v90, v2
	v_sub_f32_e32 v91, v91, v2
	v_sub_f32_e32 v92, v92, v2
	v_sub_f32_e32 v93, v93, v2
	v_sub_f32_e32 v94, v94, v2
	v_sub_f32_e32 v95, v95, v2
